# adaLN modulation vectors of the prompt rows kept in registers across the LayerNorm/modulate row loops (reloaded only for sample rows); mla_row slices requested together
# speedup vs baseline: 1.0116x; 1.0027x over previous
; DI unsigned pk2(float lo, float hi) { const hwf2_t v = {lo, hi}; const hwbf2_t b = __builtin_convertvector(v, hwbf2_t); return __builtin_bit_cast(unsigned, b); }
; DI float lo16(unsigned w) { return __uint_as_float(w << 16); }
; DI float hi16(unsigned w) { return __uint_as_float(w & 0xffff0000u); }
; DI void ln_pass(CP c, int mode, const float* gam, const float* bet, const float* modsc, const float* modsh, int bid, int nb, bool fin) {
;     ...
;     for (int r = bid * 8 + wave; r < MT; r += nb * 8) {
;         f32x4 v[4];
;         if (mode == 0) { const float* src = r < MP ? c->in[I_XP] + (size_t)r * DM : c->in[I_XS] + (size_t)(r - MP) * DM;
; #pragma unroll
;             for (int i = 0; i < 4; ++i) v[i] = *(const f32x4*)(src + lane * 4 + 256 * i); }
;         else {
; #pragma unroll
;             for (int i = 0; i < 4; ++i) { const u32x2 w = *(const u32x2*)(XB + (size_t)r * DM + lane * 4 + 256 * i); v[i] = (f32x4){lo16(w.x), hi16(w.x), lo16(w.y), hi16(w.y)}; } }
;         if (mode != 1) {
;             float s = 0.f;
; #pragma unroll
;             for (int i = 0; i < 4; ++i) s += v[i][0] + v[i][1] + v[i][2] + v[i][3];
;             const float mean = wave_sum(s) * (1.f / 1024.f); float q = 0.f;
; #pragma unroll
;             for (int i = 0; i < 4; ++i) { const f32x4 d = v[i] - mean; q += d[0] * d[0] + d[1] * d[1] + d[2] * d[2] + d[3] * d[3]; }
;             const float rstd = rsqrtf(wave_sum(q) * (1.f / 1024.f) + 1e-5f);
; #pragma unroll
;             for (int i = 0; i < 4; ++i) { const int col = lane * 4 + 256 * i; const f32x4 g = *(const f32x4*)(gam + col), b = *(const f32x4*)(bet + col);
;                 v[i] = (v[i] - mean) * rstd * g + b;
;                 if (fin) *(f32x4*)(c->out + (size_t)r * DM + col) = v[i];
;                 else { u32x2 w; w.x = pk2(v[i][0], v[i][1]); w.y = pk2(v[i][2], v[i][3]); *(u32x2*)(XB + (size_t)r * DM + col) = w; } }
;         }
;         if (modsc) { const int mr = modrow_of(r);
; #pragma unroll
;             for (int i = 0; i < 4; ++i) { const int col = lane * 4 + 256 * i; const f32x4 sc = *(const f32x4*)(modsc + (size_t)mr * 12288 + col), sh = *(const f32x4*)(modsh + (size_t)mr * 12288 + col);
;                 const f32x4 h = v[i] * (sc + 1.0f) + sh; u32x2 w; w.x = pk2(h[0], h[1]); w.y = pk2(h[2], h[3]);
;                 *(u32x2*)(H + (size_t)r * DM + col) = w; } }
.Lmini_done:
	v_readlane_b32 s6, v254, 28
	v_readlane_b32 s76, v254, 24
	v_readlane_b32 s7, v254, 29
	v_readlane_b32 s77, v254, 25
	v_readlane_b32 s88, v254, 26
	s_mov_b64 s[8:9], -1
	s_mov_b64 s[0:1], 0
	s_cmp_lt_i32 s6, 1
	s_mov_b64 s[6:7], 0
	v_readlane_b32 s89, v254, 27
	s_movk_i32 s81, 0x41ff
	s_movk_i32 s77, 0x300
	s_cbranch_scc1 .LBB0_172
	v_readlane_b32 s6, v254, 28
	s_cmp_gt_i32 s6, 1
	v_readlane_b32 s7, v254, 29
	s_cbranch_scc0 .LBB0_174
	s_cmp_eq_u32 s6, 2
	s_mov_b64 s[6:7], -1
	s_cbranch_scc0 .LBB0_171
	s_waitcnt vmcnt(0)
	v_mov_b32_e32 v9, v188
	v_readlane_b32 s6, v252, 39
	v_ashrrev_i32_e32 v6, 6, v9
	v_readlane_b32 s7, v252, 40
	v_add_u32_e32 v8, s6, v6
	s_movk_i32 s6, 0x4200
	v_cmp_gt_i32_e32 vcc, s6, v8
	s_and_saveexec_b64 s[6:7], vcc
	s_cbranch_execz .LBB0_170
	v_lshlrev_b32_e32 v0, 4, v9
	v_and_b32_e32 v0, 0x3f0, v0
	v_lshl_add_u64 v[2:3], s[20:21], 0, v[0:1]
	s_mov_b64 s[8:9], 0x5000
	v_lshl_add_u64 v[2:3], v[2:3], 0, s[8:9]
	v_readlane_b32 s8, v254, 34
	v_readlane_b32 s9, v254, 35
	v_ashrrev_i32_e32 v7, 31, v6
	s_nop 0
	v_lshl_add_u64 v[4:5], s[8:9], 0, v[0:1]
	v_readlane_b32 s8, v252, 39
	v_readlane_b32 s9, v252, 40
	v_and_b32_e32 v0, 63, v9
	s_nop 0
	v_lshl_add_u64 v[6:7], s[8:9], 0, v[6:7]
	v_lshlrev_b64 v[6:7], 11, v[6:7]
	v_lshl_or_b32 v6, v0, 3, v6
	v_lshl_add_u64 v[6:7], s[20:21], 0, v[6:7]
	s_mov_b64 s[8:9], 0x123c4000
	v_lshl_add_u64 v[6:7], v[6:7], 0, s[8:9]
	s_mov_b64 s[8:9], 0
	v_add_co_u32_e32 v18, vcc, 0xa342000, v6
	s_nop 1
	v_addc_co_u32_e32 v19, vcc, 0, v7, vcc
	global_load_dwordx2 v[92:93], v[18:19], off
	global_load_dwordx2 v[94:95], v[18:19], off offset:512
	global_load_dwordx2 v[96:97], v[18:19], off offset:1024
	global_load_dwordx2 v[98:99], v[18:19], off offset:1536
	global_load_dwordx4 v[108:111], v[2:3], off
	global_load_dwordx4 v[112:115], v[2:3], off offset:1024
	global_load_dwordx4 v[116:119], v[2:3], off offset:2048
	global_load_dwordx4 v[120:123], v[2:3], off offset:3072
	global_load_dwordx4 v[124:127], v[4:5], off
	global_load_dwordx4 v[128:131], v[4:5], off offset:1024
	global_load_dwordx4 v[132:135], v[4:5], off offset:2048
	global_load_dwordx4 v[136:139], v[4:5], off offset:3072
	s_waitcnt vmcnt(0)
	v_add_f32_e32 v108, 1.0, v108
	v_add_f32_e32 v109, 1.0, v109
	v_add_f32_e32 v110, 1.0, v110
	v_add_f32_e32 v111, 1.0, v111
	v_add_f32_e32 v112, 1.0, v112
	v_add_f32_e32 v113, 1.0, v113
	v_add_f32_e32 v114, 1.0, v114
	v_add_f32_e32 v115, 1.0, v115
	v_add_f32_e32 v116, 1.0, v116
	v_add_f32_e32 v117, 1.0, v117
	v_add_f32_e32 v118, 1.0, v118
	v_add_f32_e32 v119, 1.0, v119
	v_add_f32_e32 v120, 1.0, v120
	v_add_f32_e32 v121, 1.0, v121
	v_add_f32_e32 v122, 1.0, v122
	v_add_f32_e32 v123, 1.0, v123
.LBB0_169:
	v_add_u32_e32 v0, 0xffffc000, v8
	v_lshrrev_b32_e32 v0, 4, v0
	v_add_u32_e32 v0, 1, v0
	v_cmp_lt_i32_e32 vcc, s3, v8
	s_nop 1
	v_cndmask_b32_e32 v0, 0, v0, vcc
	v_cmp_ne_u32_e32 vcc, 0, v0
	s_cbranch_vccz .Lmh_5
	v_mad_u64_u32 v[22:23], s[12:13], v0, s86, v[2:3]
	v_mad_u64_u32 v[24:25], s[12:13], v0, s86, v[4:5]
	global_load_dwordx4 v[108:111], v[22:23], off
	global_load_dwordx4 v[112:115], v[22:23], off offset:1024
	global_load_dwordx4 v[116:119], v[22:23], off offset:2048
	global_load_dwordx4 v[120:123], v[22:23], off offset:3072
	global_load_dwordx4 v[124:127], v[24:25], off
	global_load_dwordx4 v[128:131], v[24:25], off offset:1024
	global_load_dwordx4 v[132:135], v[24:25], off offset:2048
	global_load_dwordx4 v[136:139], v[24:25], off offset:3072
	s_waitcnt vmcnt(0)
	v_add_f32_e32 v108, 1.0, v108
	v_add_f32_e32 v109, 1.0, v109
	v_add_f32_e32 v110, 1.0, v110
	v_add_f32_e32 v111, 1.0, v111
	v_add_f32_e32 v112, 1.0, v112
	v_add_f32_e32 v113, 1.0, v113
	v_add_f32_e32 v114, 1.0, v114
	v_add_f32_e32 v115, 1.0, v115
	v_add_f32_e32 v116, 1.0, v116
	v_add_f32_e32 v117, 1.0, v117
	v_add_f32_e32 v118, 1.0, v118
	v_add_f32_e32 v119, 1.0, v119
	v_add_f32_e32 v120, 1.0, v120
	v_add_f32_e32 v121, 1.0, v121
	v_add_f32_e32 v122, 1.0, v122
	v_add_f32_e32 v123, 1.0, v123
; DI unsigned pk2(float lo, float hi) { const hwf2_t v = {lo, hi}; const hwbf2_t b = __builtin_convertvector(v, hwbf2_t); return __builtin_bit_cast(unsigned, b); }
; DI float lo16(unsigned w) { return __uint_as_float(w << 16); }
; DI float hi16(unsigned w) { return __uint_as_float(w & 0xffff0000u); }
; DI float wave_sum(float v) { for (int o = 32; o >= 1; o >>= 1) v += __shfl_xor(v, o); return v; }
; DI void ln_pass(CP c, int mode, const float* gam, const float* bet, const float* modsc, const float* modsh, int bid, int nb, bool fin) {
;     ...
; #pragma unroll
;             for (int i = 0; i < 4; ++i) { const u32x2 w = *(const u32x2*)(XB + (size_t)r * DM + lane * 4 + 256 * i); v[i] = (f32x4){lo16(w.x), hi16(w.x), lo16(w.y), hi16(w.y)}; } }
;         if (mode != 1) {
;             float s = 0.f;
; #pragma unroll
;             for (int i = 0; i < 4; ++i) s += v[i][0] + v[i][1] + v[i][2] + v[i][3];
;             const float mean = wave_sum(s) * (1.f / 1024.f); float q = 0.f;
; #pragma unroll
;             for (int i = 0; i < 4; ++i) { const f32x4 d = v[i] - mean; q += d[0] * d[0] + d[1] * d[1] + d[2] * d[2] + d[3] * d[3]; }
;             const float rstd = rsqrtf(wave_sum(q) * (1.f / 1024.f) + 1e-5f);
; #pragma unroll
;             for (int i = 0; i < 4; ++i) { const int col = lane * 4 + 256 * i; const f32x4 g = *(const f32x4*)(gam + col), b = *(const f32x4*)(bet + col);
;                 v[i] = (v[i] - mean) * rstd * g + b;
;                 if (fin) *(f32x4*)(c->out + (size_t)r * DM + col) = v[i];
;                 else { u32x2 w; w.x = pk2(v[i][0], v[i][1]); w.y = pk2(v[i][2], v[i][3]); *(u32x2*)(XB + (size_t)r * DM + col) = w; } }
;         }
;         if (modsc) { const int mr = modrow_of(r);
; #pragma unroll
;             for (int i = 0; i < 4; ++i) { const int col = lane * 4 + 256 * i; const f32x4 sc = *(const f32x4*)(modsc + (size_t)mr * 12288 + col), sh = *(const f32x4*)(modsh + (size_t)mr * 12288 + col);
;                 const f32x4 h = v[i] * (sc + 1.0f) + sh; u32x2 w; w.x = pk2(h[0], h[1]); w.y = pk2(h[2], h[3]);
;                 *(u32x2*)(H + (size_t)r * DM + col) = w; } }
.Lmh_5:
	s_waitcnt vmcnt(4)
	v_lshl_add_u64 v[48:49], v[18:19], 0, s[44:45]
	global_load_dwordx2 v[100:101], v[48:49], off
	global_load_dwordx2 v[102:103], v[48:49], off offset:512
	global_load_dwordx2 v[104:105], v[48:49], off offset:1024
	global_load_dwordx2 v[106:107], v[48:49], off offset:1536
	v_lshlrev_b32_e32 v140, 16, v92
	v_and_b32_e32 v141, 0xffff0000, v92
	v_lshlrev_b32_e32 v142, 16, v93
	v_and_b32_e32 v143, 0xffff0000, v93
	v_lshlrev_b32_e32 v144, 16, v94
	v_and_b32_e32 v145, 0xffff0000, v94
	v_lshlrev_b32_e32 v146, 16, v95
	v_and_b32_e32 v147, 0xffff0000, v95
	v_lshlrev_b32_e32 v148, 16, v96
	v_and_b32_e32 v149, 0xffff0000, v96
	v_lshlrev_b32_e32 v150, 16, v97
	v_and_b32_e32 v151, 0xffff0000, v97
	v_lshlrev_b32_e32 v152, 16, v98
	v_and_b32_e32 v153, 0xffff0000, v98
	v_lshlrev_b32_e32 v154, 16, v99
	v_and_b32_e32 v155, 0xffff0000, v99
	v_fma_f32 v140, v108, v140, v124
	v_fma_f32 v141, v109, v141, v125
	v_fma_f32 v142, v110, v142, v126
	v_fma_f32 v143, v111, v143, v127
	v_fma_f32 v144, v112, v144, v128
	v_fma_f32 v145, v113, v145, v129
	v_fma_f32 v146, v114, v146, v130
	v_fma_f32 v147, v115, v147, v131
	v_fma_f32 v148, v116, v148, v132
	v_fma_f32 v149, v117, v149, v133
	v_fma_f32 v150, v118, v150, v134
	v_fma_f32 v151, v119, v151, v135
	v_fma_f32 v152, v120, v152, v136
	v_fma_f32 v153, v121, v153, v137
	v_fma_f32 v154, v122, v154, v138
	v_fma_f32 v155, v123, v155, v139
	v_cvt_pk_bf16_f32 v50, v140, v141
	v_cvt_pk_bf16_f32 v51, v142, v143
	global_store_dwordx2 v[6:7], v[50:51], off
	v_cvt_pk_bf16_f32 v52, v144, v145
	v_cvt_pk_bf16_f32 v53, v146, v147
	global_store_dwordx2 v[6:7], v[52:53], off offset:512
	v_cvt_pk_bf16_f32 v54, v148, v149
	v_cvt_pk_bf16_f32 v55, v150, v151
	global_store_dwordx2 v[6:7], v[54:55], off offset:1024
	v_cvt_pk_bf16_f32 v56, v152, v153
	v_cvt_pk_bf16_f32 v57, v154, v155
	global_store_dwordx2 v[6:7], v[56:57], off offset:1536
	v_add_u32_e32 v8, s76, v8
	v_mov_b32_e32 v18, v48
	v_mov_b32_e32 v19, v49
	v_lshl_add_u64 v[6:7], v[6:7], 0, s[44:45]
	v_cmp_lt_i32_e32 vcc, s81, v8
	s_or_b64 s[8:9], vcc, s[8:9]
	s_andn2_b64 exec, exec, s[8:9]
	s_cbranch_execz .LBB0_170
	v_add_u32_e32 v0, 0xffffc000, v8
	v_lshrrev_b32_e32 v0, 4, v0
	v_add_u32_e32 v0, 1, v0
	v_cmp_lt_i32_e32 vcc, s3, v8
	s_nop 1
	v_cndmask_b32_e32 v0, 0, v0, vcc
	v_cmp_ne_u32_e32 vcc, 0, v0
	s_cbranch_vccz .Lmh_6
	v_mad_u64_u32 v[22:23], s[12:13], v0, s86, v[2:3]
	v_mad_u64_u32 v[24:25], s[12:13], v0, s86, v[4:5]
	global_load_dwordx4 v[108:111], v[22:23], off
	global_load_dwordx4 v[112:115], v[22:23], off offset:1024
	global_load_dwordx4 v[116:119], v[22:23], off offset:2048
	global_load_dwordx4 v[120:123], v[22:23], off offset:3072
	global_load_dwordx4 v[124:127], v[24:25], off
	global_load_dwordx4 v[128:131], v[24:25], off offset:1024
	global_load_dwordx4 v[132:135], v[24:25], off offset:2048
	global_load_dwordx4 v[136:139], v[24:25], off offset:3072
	s_waitcnt vmcnt(0)
	v_add_f32_e32 v108, 1.0, v108
	v_add_f32_e32 v109, 1.0, v109
	v_add_f32_e32 v110, 1.0, v110
	v_add_f32_e32 v111, 1.0, v111
	v_add_f32_e32 v112, 1.0, v112
	v_add_f32_e32 v113, 1.0, v113
	v_add_f32_e32 v114, 1.0, v114
	v_add_f32_e32 v115, 1.0, v115
	v_add_f32_e32 v116, 1.0, v116
	v_add_f32_e32 v117, 1.0, v117
	v_add_f32_e32 v118, 1.0, v118
	v_add_f32_e32 v119, 1.0, v119
	v_add_f32_e32 v120, 1.0, v120
	v_add_f32_e32 v121, 1.0, v121
	v_add_f32_e32 v122, 1.0, v122
	v_add_f32_e32 v123, 1.0, v123
.Lmh_6:
	s_waitcnt vmcnt(4)
	v_lshl_add_u64 v[48:49], v[18:19], 0, s[44:45]
	global_load_dwordx2 v[92:93], v[48:49], off
	global_load_dwordx2 v[94:95], v[48:49], off offset:512
	global_load_dwordx2 v[96:97], v[48:49], off offset:1024
	global_load_dwordx2 v[98:99], v[48:49], off offset:1536
	v_lshlrev_b32_e32 v140, 16, v100
	v_and_b32_e32 v141, 0xffff0000, v100
	v_lshlrev_b32_e32 v142, 16, v101
	v_and_b32_e32 v143, 0xffff0000, v101
	v_lshlrev_b32_e32 v144, 16, v102
	v_and_b32_e32 v145, 0xffff0000, v102
	v_lshlrev_b32_e32 v146, 16, v103
	v_and_b32_e32 v147, 0xffff0000, v103
	v_lshlrev_b32_e32 v148, 16, v104
	v_and_b32_e32 v149, 0xffff0000, v104
	v_lshlrev_b32_e32 v150, 16, v105
	v_and_b32_e32 v151, 0xffff0000, v105
	v_lshlrev_b32_e32 v152, 16, v106
	v_and_b32_e32 v153, 0xffff0000, v106
	v_lshlrev_b32_e32 v154, 16, v107
	v_and_b32_e32 v155, 0xffff0000, v107
	v_fma_f32 v140, v108, v140, v124
	v_fma_f32 v141, v109, v141, v125
	v_fma_f32 v142, v110, v142, v126
	v_fma_f32 v143, v111, v143, v127
	v_fma_f32 v144, v112, v144, v128
	v_fma_f32 v145, v113, v145, v129
	v_fma_f32 v146, v114, v146, v130
	v_fma_f32 v147, v115, v147, v131
	v_fma_f32 v148, v116, v148, v132
	v_fma_f32 v149, v117, v149, v133
	v_fma_f32 v150, v118, v150, v134
	v_fma_f32 v151, v119, v151, v135
	v_fma_f32 v152, v120, v152, v136
	v_fma_f32 v153, v121, v153, v137
	v_fma_f32 v154, v122, v154, v138
	v_fma_f32 v155, v123, v155, v139
	v_cvt_pk_bf16_f32 v50, v140, v141
	v_cvt_pk_bf16_f32 v51, v142, v143
	global_store_dwordx2 v[6:7], v[50:51], off
	v_cvt_pk_bf16_f32 v52, v144, v145
	v_cvt_pk_bf16_f32 v53, v146, v147
	global_store_dwordx2 v[6:7], v[52:53], off offset:512
	v_cvt_pk_bf16_f32 v54, v148, v149
	v_cvt_pk_bf16_f32 v55, v150, v151
	global_store_dwordx2 v[6:7], v[54:55], off offset:1024
	v_cvt_pk_bf16_f32 v56, v152, v153
	v_cvt_pk_bf16_f32 v57, v154, v155
	global_store_dwordx2 v[6:7], v[56:57], off offset:1536
	v_add_u32_e32 v8, s76, v8
	v_mov_b32_e32 v18, v48
	v_mov_b32_e32 v19, v49
	v_lshl_add_u64 v[6:7], v[6:7], 0, s[44:45]
	v_cmp_lt_i32_e32 vcc, s81, v8
	s_or_b64 s[8:9], vcc, s[8:9]
	s_andn2_b64 exec, exec, s[8:9]
	s_cbranch_execnz .LBB0_169

; DI unsigned pk2(float lo, float hi) { const hwf2_t v = {lo, hi}; const hwbf2_t b = __builtin_convertvector(v, hwbf2_t); return __builtin_bit_cast(unsigned, b); }
; DI float lo16(unsigned w) { return __uint_as_float(w << 16); }
; DI float hi16(unsigned w) { return __uint_as_float(w & 0xffff0000u); }
; DI void ln_pass(CP c, int mode, const float* gam, const float* bet, const float* modsc, const float* modsh, int bid, int nb, bool fin) {
;     ...
;     for (int r = bid * 8 + wave; r < MT; r += nb * 8) {
;         f32x4 v[4];
;         if (mode == 0) { const float* src = r < MP ? c->in[I_XP] + (size_t)r * DM : c->in[I_XS] + (size_t)(r - MP) * DM;
; #pragma unroll
;             for (int i = 0; i < 4; ++i) v[i] = *(const f32x4*)(src + lane * 4 + 256 * i); }
;         else {
; #pragma unroll
;             for (int i = 0; i < 4; ++i) { const u32x2 w = *(const u32x2*)(XB + (size_t)r * DM + lane * 4 + 256 * i); v[i] = (f32x4){lo16(w.x), hi16(w.x), lo16(w.y), hi16(w.y)}; } }
;         if (mode != 1) {
;             float s = 0.f;
; #pragma unroll
;             for (int i = 0; i < 4; ++i) s += v[i][0] + v[i][1] + v[i][2] + v[i][3];
;             const float mean = wave_sum(s) * (1.f / 1024.f); float q = 0.f;
; #pragma unroll
;             for (int i = 0; i < 4; ++i) { const f32x4 d = v[i] - mean; q += d[0] * d[0] + d[1] * d[1] + d[2] * d[2] + d[3] * d[3]; }
;             const float rstd = rsqrtf(wave_sum(q) * (1.f / 1024.f) + 1e-5f);
; #pragma unroll
;             for (int i = 0; i < 4; ++i) { const int col = lane * 4 + 256 * i; const f32x4 g = *(const f32x4*)(gam + col), b = *(const f32x4*)(bet + col);
;                 v[i] = (v[i] - mean) * rstd * g + b;
;                 if (fin) *(f32x4*)(c->out + (size_t)r * DM + col) = v[i];
;                 else { u32x2 w; w.x = pk2(v[i][0], v[i][1]); w.y = pk2(v[i][2], v[i][3]); *(u32x2*)(XB + (size_t)r * DM + col) = w; } }
;         }
;         if (modsc) { const int mr = modrow_of(r);
; #pragma unroll
;             for (int i = 0; i < 4; ++i) { const int col = lane * 4 + 256 * i; const f32x4 sc = *(const f32x4*)(modsc + (size_t)mr * 12288 + col), sh = *(const f32x4*)(modsh + (size_t)mr * 12288 + col);
;                 const f32x4 h = v[i] * (sc + 1.0f) + sh; u32x2 w; w.x = pk2(h[0], h[1]); w.y = pk2(h[2], h[3]);
;                 *(u32x2*)(H + (size_t)r * DM + col) = w; } }
.LBB0_412:
	s_andn2_b64 vcc, exec, s[6:7]
	s_cbranch_vccnz .LBB0_427
	v_mov_b32_e32 v12, v188
	v_readlane_b32 s0, v252, 39
	s_waitcnt vmcnt(0)
	v_ashrrev_i32_e32 v10, 6, v12
	v_readlane_b32 s1, v252, 40
	v_add_u32_e32 v30, s0, v10
	s_movk_i32 s0, 0x4200
	v_cmp_gt_i32_e32 vcc, s0, v30
	s_and_saveexec_b64 s[0:1], vcc
	s_mov_b32 s12, 0x800000
	s_cbranch_execz .LBB0_416
	v_and_b32_e32 v6, 64, v196
	v_add_u32_e32 v6, 64, v6
	v_xor_b32_e32 v7, 32, v196
	v_cmp_lt_i32_e32 vcc, v7, v6
	v_lshlrev_b32_e32 v0, 4, v12
	v_and_b32_e32 v0, 0x3f0, v0
	v_cndmask_b32_e32 v7, v196, v7, vcc
	v_lshlrev_b32_e32 v31, 2, v7
	v_xor_b32_e32 v7, 16, v196
	v_cmp_lt_i32_e32 vcc, v7, v6
	v_lshl_add_u64 v[8:9], s[20:21], 0, v[0:1]
	s_mov_b64 s[6:7], 0xb000
	v_cndmask_b32_e32 v7, v196, v7, vcc
	v_lshlrev_b32_e32 v32, 2, v7
	v_xor_b32_e32 v7, 8, v196
	v_cmp_lt_i32_e32 vcc, v7, v6
	v_ashrrev_i32_e32 v11, 31, v10
	s_waitcnt lgkmcnt(0)
	v_lshl_add_u64 v[2:3], s[40:41], 0, v[0:1]
	v_cndmask_b32_e32 v7, v196, v7, vcc
	v_lshlrev_b32_e32 v33, 2, v7
	v_xor_b32_e32 v7, 4, v196
	v_cmp_lt_i32_e32 vcc, v7, v6
	v_lshl_add_u64 v[4:5], s[42:43], 0, v[0:1]
	v_and_b32_e32 v0, 63, v12
	v_cndmask_b32_e32 v7, v196, v7, vcc
	v_lshlrev_b32_e32 v34, 2, v7
	v_xor_b32_e32 v7, 2, v196
	v_cmp_lt_i32_e32 vcc, v7, v6
	s_nop 1
	v_cndmask_b32_e32 v7, v196, v7, vcc
	v_lshlrev_b32_e32 v35, 2, v7
	v_xor_b32_e32 v7, 1, v196
	v_cmp_lt_i32_e32 vcc, v7, v6
	s_nop 1
	v_cndmask_b32_e32 v6, v196, v7, vcc
	v_lshlrev_b32_e32 v36, 2, v6
	v_lshl_add_u64 v[6:7], v[8:9], 0, s[6:7]
	s_mov_b64 s[6:7], 0xa000
	v_lshl_add_u64 v[8:9], v[8:9], 0, s[6:7]
	v_readlane_b32 s6, v252, 39
	v_readlane_b32 s7, v252, 40
	s_nop 1
	v_lshl_add_u64 v[10:11], s[6:7], 0, v[10:11]
	v_lshlrev_b64 v[10:11], 11, v[10:11]
	v_lshl_or_b32 v10, v0, 3, v10
	v_lshl_add_u64 v[10:11], s[20:21], 0, v[10:11]
	s_mov_b64 s[6:7], 0x123c4000
	v_lshl_add_u64 v[10:11], v[10:11], 0, s[6:7]
	s_mov_b64 s[6:7], 0
	global_load_dwordx4 v[60:63], v[2:3], off
	global_load_dwordx4 v[64:67], v[2:3], off offset:1024
	global_load_dwordx4 v[68:71], v[2:3], off offset:2048
	global_load_dwordx4 v[72:75], v[2:3], off offset:3072
	global_load_dwordx4 v[76:79], v[4:5], off
	global_load_dwordx4 v[80:83], v[4:5], off offset:1024
	global_load_dwordx4 v[84:87], v[4:5], off offset:2048
	global_load_dwordx4 v[88:91], v[4:5], off offset:3072
	v_add_co_u32_e32 v12, vcc, 0xa342000, v10
	s_nop 1
	v_addc_co_u32_e32 v13, vcc, 0, v11, vcc
	global_load_dwordx2 v[92:93], v[12:13], off
	global_load_dwordx2 v[94:95], v[12:13], off offset:512
	global_load_dwordx2 v[96:97], v[12:13], off offset:1024
	global_load_dwordx2 v[98:99], v[12:13], off offset:1536
	global_load_dwordx4 v[108:111], v[6:7], off
	global_load_dwordx4 v[112:115], v[6:7], off offset:1024
	global_load_dwordx4 v[116:119], v[6:7], off offset:2048
	global_load_dwordx4 v[120:123], v[6:7], off offset:3072
	global_load_dwordx4 v[124:127], v[8:9], off
	global_load_dwordx4 v[128:131], v[8:9], off offset:1024
	global_load_dwordx4 v[132:135], v[8:9], off offset:2048
	global_load_dwordx4 v[136:139], v[8:9], off offset:3072
	s_waitcnt vmcnt(0)
	v_add_f32_e32 v108, 1.0, v108
	v_add_f32_e32 v109, 1.0, v109
	v_add_f32_e32 v110, 1.0, v110
	v_add_f32_e32 v111, 1.0, v111
	v_add_f32_e32 v112, 1.0, v112
	v_add_f32_e32 v113, 1.0, v113
	v_add_f32_e32 v114, 1.0, v114
	v_add_f32_e32 v115, 1.0, v115
	v_add_f32_e32 v116, 1.0, v116
	v_add_f32_e32 v117, 1.0, v117
	v_add_f32_e32 v118, 1.0, v118
	v_add_f32_e32 v119, 1.0, v119
	v_add_f32_e32 v120, 1.0, v120
	v_add_f32_e32 v121, 1.0, v121
	v_add_f32_e32 v122, 1.0, v122
	v_add_f32_e32 v123, 1.0, v123
.LBB0_415:
	v_add_u32_e32 v0, 0xffffc000, v30
	v_lshrrev_b32_e32 v0, 4, v0
	v_add_u32_e32 v0, 1, v0
	v_cmp_lt_i32_e32 vcc, s3, v30
	s_nop 1
	v_cndmask_b32_e32 v0, 0, v0, vcc
	v_cmp_ne_u32_e32 vcc, 0, v0
	s_cbranch_vccz .Lmh_3
	v_mad_u64_u32 v[24:25], s[8:9], v0, s86, v[6:7]
	v_mad_u64_u32 v[46:47], s[8:9], v0, s86, v[8:9]
	global_load_dwordx4 v[108:111], v[24:25], off
	global_load_dwordx4 v[112:115], v[24:25], off offset:1024
	global_load_dwordx4 v[116:119], v[24:25], off offset:2048
	global_load_dwordx4 v[120:123], v[24:25], off offset:3072
	global_load_dwordx4 v[124:127], v[46:47], off
	global_load_dwordx4 v[128:131], v[46:47], off offset:1024
	global_load_dwordx4 v[132:135], v[46:47], off offset:2048
	global_load_dwordx4 v[136:139], v[46:47], off offset:3072
	s_waitcnt vmcnt(0)
	v_add_f32_e32 v108, 1.0, v108
	v_add_f32_e32 v109, 1.0, v109
	v_add_f32_e32 v110, 1.0, v110
	v_add_f32_e32 v111, 1.0, v111
	v_add_f32_e32 v112, 1.0, v112
	v_add_f32_e32 v113, 1.0, v113
	v_add_f32_e32 v114, 1.0, v114
	v_add_f32_e32 v115, 1.0, v115
	v_add_f32_e32 v116, 1.0, v116
	v_add_f32_e32 v117, 1.0, v117
	v_add_f32_e32 v118, 1.0, v118
	v_add_f32_e32 v119, 1.0, v119
	v_add_f32_e32 v120, 1.0, v120
	v_add_f32_e32 v121, 1.0, v121
	v_add_f32_e32 v122, 1.0, v122
	v_add_f32_e32 v123, 1.0, v123
; DI unsigned pk2(float lo, float hi) { const hwf2_t v = {lo, hi}; const hwbf2_t b = __builtin_convertvector(v, hwbf2_t); return __builtin_bit_cast(unsigned, b); }
; DI float wave_sum(float v) { for (int o = 32; o >= 1; o >>= 1) v += __shfl_xor(v, o); return v; }
; DI void ln_pass(CP c, int mode, const float* gam, const float* bet, const float* modsc, const float* modsh, int bid, int nb, bool fin) {
;     ...
;         if (mode != 1) {
;             float s = 0.f;
; #pragma unroll
;             for (int i = 0; i < 4; ++i) s += v[i][0] + v[i][1] + v[i][2] + v[i][3];
;             const float mean = wave_sum(s) * (1.f / 1024.f); float q = 0.f;
; #pragma unroll
;             for (int i = 0; i < 4; ++i) { const f32x4 d = v[i] - mean; q += d[0] * d[0] + d[1] * d[1] + d[2] * d[2] + d[3] * d[3]; }
;             const float rstd = rsqrtf(wave_sum(q) * (1.f / 1024.f) + 1e-5f);
; #pragma unroll
;             for (int i = 0; i < 4; ++i) { const int col = lane * 4 + 256 * i; const f32x4 g = *(const f32x4*)(gam + col), b = *(const f32x4*)(bet + col);
;                 v[i] = (v[i] - mean) * rstd * g + b;
;                 if (fin) *(f32x4*)(c->out + (size_t)r * DM + col) = v[i];
;                 else { u32x2 w; w.x = pk2(v[i][0], v[i][1]); w.y = pk2(v[i][2], v[i][3]); *(u32x2*)(XB + (size_t)r * DM + col) = w; } }
;         }
;         if (modsc) { const int mr = modrow_of(r);
; #pragma unroll
;             for (int i = 0; i < 4; ++i) { const int col = lane * 4 + 256 * i; const f32x4 sc = *(const f32x4*)(modsc + (size_t)mr * 12288 + col), sh = *(const f32x4*)(modsh + (size_t)mr * 12288 + col);
;                 const f32x4 h = v[i] * (sc + 1.0f) + sh; u32x2 w; w.x = pk2(h[0], h[1]); w.y = pk2(h[2], h[3]);
;                 *(u32x2*)(H + (size_t)r * DM + col) = w; } }
.Lmh_3:
	s_waitcnt vmcnt(8)
	v_lshl_add_u64 v[48:49], v[12:13], 0, s[44:45]
	global_load_dwordx2 v[100:101], v[48:49], off
	global_load_dwordx2 v[102:103], v[48:49], off offset:512
	global_load_dwordx2 v[104:105], v[48:49], off offset:1024
	global_load_dwordx2 v[106:107], v[48:49], off offset:1536
	v_lshlrev_b32_e32 v140, 16, v92
	v_and_b32_e32 v141, 0xffff0000, v92
	v_lshlrev_b32_e32 v142, 16, v93
	v_and_b32_e32 v143, 0xffff0000, v93
	v_lshlrev_b32_e32 v144, 16, v94
	v_and_b32_e32 v145, 0xffff0000, v94
	v_lshlrev_b32_e32 v146, 16, v95
	v_and_b32_e32 v147, 0xffff0000, v95
	v_lshlrev_b32_e32 v148, 16, v96
	v_and_b32_e32 v149, 0xffff0000, v96
	v_lshlrev_b32_e32 v150, 16, v97
	v_and_b32_e32 v151, 0xffff0000, v97
	v_lshlrev_b32_e32 v152, 16, v98
	v_and_b32_e32 v153, 0xffff0000, v98
	v_lshlrev_b32_e32 v154, 16, v99
	v_and_b32_e32 v155, 0xffff0000, v99
	v_add_f32_e32 v0, v140, v141
	v_add_f32_e32 v0, v0, v142
	v_add_f32_e32 v0, v0, v143
	v_add_f32_e32 v0, v0, v144
	v_add_f32_e32 v0, v0, v145
	v_add_f32_e32 v0, v0, v146
	v_add_f32_e32 v0, v0, v147
	v_add_f32_e32 v0, v0, v148
	v_add_f32_e32 v0, v0, v149
	v_add_f32_e32 v0, v0, v150
	v_add_f32_e32 v0, v0, v151
	v_add_f32_e32 v0, v0, v152
	v_add_f32_e32 v0, v0, v153
	v_add_f32_e32 v0, v0, v154
	v_add_f32_e32 v0, v0, v155
	ds_bpermute_b32 v14, v31, v0
	s_waitcnt lgkmcnt(0)
	v_add_f32_e32 v0, v0, v14
	ds_bpermute_b32 v14, v32, v0
	s_waitcnt lgkmcnt(0)
	v_add_f32_e32 v0, v0, v14
	ds_bpermute_b32 v14, v33, v0
	s_waitcnt lgkmcnt(0)
	v_add_f32_e32 v0, v0, v14
	ds_bpermute_b32 v14, v34, v0
	s_waitcnt lgkmcnt(0)
	v_add_f32_e32 v0, v0, v14
	ds_bpermute_b32 v14, v35, v0
	s_waitcnt lgkmcnt(0)
	v_add_f32_e32 v0, v0, v14
	ds_bpermute_b32 v14, v36, v0
	s_waitcnt lgkmcnt(0)
	v_add_f32_e32 v0, v0, v14
	v_fmac_f32_e32 v140, 0xba800000, v0
	v_fmac_f32_e32 v141, 0xba800000, v0
	v_fmac_f32_e32 v142, 0xba800000, v0
	v_fmac_f32_e32 v143, 0xba800000, v0
	v_fmac_f32_e32 v144, 0xba800000, v0
	v_fmac_f32_e32 v145, 0xba800000, v0
	v_fmac_f32_e32 v146, 0xba800000, v0
	v_fmac_f32_e32 v147, 0xba800000, v0
	v_fmac_f32_e32 v148, 0xba800000, v0
	v_fmac_f32_e32 v149, 0xba800000, v0
	v_fmac_f32_e32 v150, 0xba800000, v0
	v_fmac_f32_e32 v151, 0xba800000, v0
	v_fmac_f32_e32 v152, 0xba800000, v0
	v_fmac_f32_e32 v153, 0xba800000, v0
	v_fmac_f32_e32 v154, 0xba800000, v0
	v_fmac_f32_e32 v155, 0xba800000, v0
	v_mul_f32_e32 v15, v140, v140
	v_fmac_f32_e32 v15, v141, v141
	v_fmac_f32_e32 v15, v142, v142
	v_fmac_f32_e32 v15, v143, v143
	v_fmac_f32_e32 v15, v144, v144
	v_fmac_f32_e32 v15, v145, v145
	v_fmac_f32_e32 v15, v146, v146
	v_fmac_f32_e32 v15, v147, v147
	v_fmac_f32_e32 v15, v148, v148
	v_fmac_f32_e32 v15, v149, v149
	v_fmac_f32_e32 v15, v150, v150
	v_fmac_f32_e32 v15, v151, v151
	v_fmac_f32_e32 v15, v152, v152
	v_fmac_f32_e32 v15, v153, v153
	v_fmac_f32_e32 v15, v154, v154
	v_fmac_f32_e32 v15, v155, v155
	ds_bpermute_b32 v14, v31, v15
	s_waitcnt lgkmcnt(0)
	v_add_f32_e32 v15, v15, v14
	ds_bpermute_b32 v14, v32, v15
	s_waitcnt lgkmcnt(0)
	v_add_f32_e32 v15, v15, v14
	ds_bpermute_b32 v14, v33, v15
	s_waitcnt lgkmcnt(0)
	v_add_f32_e32 v15, v15, v14
	ds_bpermute_b32 v14, v34, v15
	s_waitcnt lgkmcnt(0)
	v_add_f32_e32 v15, v15, v14
	ds_bpermute_b32 v14, v35, v15
	s_waitcnt lgkmcnt(0)
	v_add_f32_e32 v15, v15, v14
	ds_bpermute_b32 v14, v36, v15
	s_waitcnt lgkmcnt(0)
	v_add_f32_e32 v15, v15, v14
	v_fmamk_f32 v15, v15, 0x3a800000, v189
	v_rsq_f32_e32 v15, v15
	s_nop 0
	v_mul_f32_e32 v140, v140, v15
	v_mul_f32_e32 v141, v141, v15
	v_mul_f32_e32 v142, v142, v15
	v_mul_f32_e32 v143, v143, v15
	v_mul_f32_e32 v144, v144, v15
	v_mul_f32_e32 v145, v145, v15
	v_mul_f32_e32 v146, v146, v15
	v_mul_f32_e32 v147, v147, v15
	v_mul_f32_e32 v148, v148, v15
	v_mul_f32_e32 v149, v149, v15
	v_mul_f32_e32 v150, v150, v15
	v_mul_f32_e32 v151, v151, v15
	v_mul_f32_e32 v152, v152, v15
	v_mul_f32_e32 v153, v153, v15
	v_mul_f32_e32 v154, v154, v15
	v_mul_f32_e32 v155, v155, v15
	v_fma_f32 v140, v60, v140, v76
	v_fma_f32 v141, v61, v141, v77
	v_fma_f32 v142, v62, v142, v78
	v_fma_f32 v143, v63, v143, v79
	v_fma_f32 v144, v64, v144, v80
	v_fma_f32 v145, v65, v145, v81
	v_fma_f32 v146, v66, v146, v82
	v_fma_f32 v147, v67, v147, v83
	v_fma_f32 v148, v68, v148, v84
	v_fma_f32 v149, v69, v149, v85
	v_fma_f32 v150, v70, v150, v86
	v_fma_f32 v151, v71, v151, v87
	v_fma_f32 v152, v72, v152, v88
	v_fma_f32 v153, v73, v153, v89
	v_fma_f32 v154, v74, v154, v90
	v_fma_f32 v155, v75, v155, v91
	v_cvt_pk_bf16_f32 v16, v140, v141
	v_cvt_pk_bf16_f32 v17, v142, v143
	global_store_dwordx2 v[12:13], v[16:17], off
	v_cvt_pk_bf16_f32 v18, v144, v145
	v_cvt_pk_bf16_f32 v19, v146, v147
	global_store_dwordx2 v[12:13], v[18:19], off offset:512
	v_cvt_pk_bf16_f32 v20, v148, v149
	v_cvt_pk_bf16_f32 v21, v150, v151
	global_store_dwordx2 v[12:13], v[20:21], off offset:1024
	v_cvt_pk_bf16_f32 v22, v152, v153
	v_cvt_pk_bf16_f32 v23, v154, v155
	global_store_dwordx2 v[12:13], v[22:23], off offset:1536
	v_fma_f32 v140, v108, v140, v124
	v_fma_f32 v141, v109, v141, v125
	v_fma_f32 v142, v110, v142, v126
	v_fma_f32 v143, v111, v143, v127
	v_fma_f32 v144, v112, v144, v128
	v_fma_f32 v145, v113, v145, v129
	v_fma_f32 v146, v114, v146, v130
	v_fma_f32 v147, v115, v147, v131
	v_fma_f32 v148, v116, v148, v132
	v_fma_f32 v149, v117, v149, v133
	v_fma_f32 v150, v118, v150, v134
	v_fma_f32 v151, v119, v151, v135
	v_fma_f32 v152, v120, v152, v136
	v_fma_f32 v153, v121, v153, v137
	v_fma_f32 v154, v122, v154, v138
	v_fma_f32 v155, v123, v155, v139
	v_cvt_pk_bf16_f32 v50, v140, v141
	v_cvt_pk_bf16_f32 v51, v142, v143
	global_store_dwordx2 v[10:11], v[50:51], off
	v_cvt_pk_bf16_f32 v52, v144, v145
	v_cvt_pk_bf16_f32 v53, v146, v147
	global_store_dwordx2 v[10:11], v[52:53], off offset:512
	v_cvt_pk_bf16_f32 v54, v148, v149
	v_cvt_pk_bf16_f32 v55, v150, v151
	global_store_dwordx2 v[10:11], v[54:55], off offset:1024
	v_cvt_pk_bf16_f32 v56, v152, v153
	v_cvt_pk_bf16_f32 v57, v154, v155
	global_store_dwordx2 v[10:11], v[56:57], off offset:1536
	v_add_u32_e32 v30, s76, v30
	v_mov_b32_e32 v12, v48
	v_mov_b32_e32 v13, v49
	v_lshl_add_u64 v[10:11], v[10:11], 0, s[44:45]
	v_cmp_lt_i32_e32 vcc, s81, v30
	s_or_b64 s[6:7], vcc, s[6:7]
	s_andn2_b64 exec, exec, s[6:7]
	s_cbranch_execz .LBB0_416
; DI void ln_pass(CP c, int mode, const float* gam, const float* bet, const float* modsc, const float* modsh, int bid, int nb, bool fin) {
;     ...
;         if (modsc) { const int mr = modrow_of(r);
; #pragma unroll
;             for (int i = 0; i < 4; ++i) { const int col = lane * 4 + 256 * i; const f32x4 sc = *(const f32x4*)(modsc + (size_t)mr * 12288 + col), sh = *(const f32x4*)(modsh + (size_t)mr * 12288 + col);
	v_add_u32_e32 v0, 0xffffc000, v30
	v_lshrrev_b32_e32 v0, 4, v0
	v_add_u32_e32 v0, 1, v0
	v_cmp_lt_i32_e32 vcc, s3, v30
	s_nop 1
	v_cndmask_b32_e32 v0, 0, v0, vcc
	v_cmp_ne_u32_e32 vcc, 0, v0
	s_cbranch_vccz .Lmh_4
	v_mad_u64_u32 v[24:25], s[8:9], v0, s86, v[6:7]
	v_mad_u64_u32 v[46:47], s[8:9], v0, s86, v[8:9]
	global_load_dwordx4 v[108:111], v[24:25], off
	global_load_dwordx4 v[112:115], v[24:25], off offset:1024
	global_load_dwordx4 v[116:119], v[24:25], off offset:2048
	global_load_dwordx4 v[120:123], v[24:25], off offset:3072
	global_load_dwordx4 v[124:127], v[46:47], off
	global_load_dwordx4 v[128:131], v[46:47], off offset:1024
	global_load_dwordx4 v[132:135], v[46:47], off offset:2048
	global_load_dwordx4 v[136:139], v[46:47], off offset:3072
	s_waitcnt vmcnt(0)
	v_add_f32_e32 v108, 1.0, v108
	v_add_f32_e32 v109, 1.0, v109
	v_add_f32_e32 v110, 1.0, v110
	v_add_f32_e32 v111, 1.0, v111
	v_add_f32_e32 v112, 1.0, v112
	v_add_f32_e32 v113, 1.0, v113
	v_add_f32_e32 v114, 1.0, v114
	v_add_f32_e32 v115, 1.0, v115
	v_add_f32_e32 v116, 1.0, v116
	v_add_f32_e32 v117, 1.0, v117
	v_add_f32_e32 v118, 1.0, v118
	v_add_f32_e32 v119, 1.0, v119
	v_add_f32_e32 v120, 1.0, v120
	v_add_f32_e32 v121, 1.0, v121
	v_add_f32_e32 v122, 1.0, v122
	v_add_f32_e32 v123, 1.0, v123
; DI unsigned pk2(float lo, float hi) { const hwf2_t v = {lo, hi}; const hwbf2_t b = __builtin_convertvector(v, hwbf2_t); return __builtin_bit_cast(unsigned, b); }
; DI float wave_sum(float v) { for (int o = 32; o >= 1; o >>= 1) v += __shfl_xor(v, o); return v; }
; DI void ln_pass(CP c, int mode, const float* gam, const float* bet, const float* modsc, const float* modsh, int bid, int nb, bool fin) {
;     ...
;         if (mode != 1) {
;             float s = 0.f;
; #pragma unroll
;             for (int i = 0; i < 4; ++i) s += v[i][0] + v[i][1] + v[i][2] + v[i][3];
;             const float mean = wave_sum(s) * (1.f / 1024.f); float q = 0.f;
; #pragma unroll
;             for (int i = 0; i < 4; ++i) { const f32x4 d = v[i] - mean; q += d[0] * d[0] + d[1] * d[1] + d[2] * d[2] + d[3] * d[3]; }
;             const float rstd = rsqrtf(wave_sum(q) * (1.f / 1024.f) + 1e-5f);
; #pragma unroll
;             for (int i = 0; i < 4; ++i) { const int col = lane * 4 + 256 * i; const f32x4 g = *(const f32x4*)(gam + col), b = *(const f32x4*)(bet + col);
;                 v[i] = (v[i] - mean) * rstd * g + b;
;                 if (fin) *(f32x4*)(c->out + (size_t)r * DM + col) = v[i];
;                 else { u32x2 w; w.x = pk2(v[i][0], v[i][1]); w.y = pk2(v[i][2], v[i][3]); *(u32x2*)(XB + (size_t)r * DM + col) = w; } }
;         }
;         if (modsc) { const int mr = modrow_of(r);
; #pragma unroll
;             for (int i = 0; i < 4; ++i) { const int col = lane * 4 + 256 * i; const f32x4 sc = *(const f32x4*)(modsc + (size_t)mr * 12288 + col), sh = *(const f32x4*)(modsh + (size_t)mr * 12288 + col);
;                 const f32x4 h = v[i] * (sc + 1.0f) + sh; u32x2 w; w.x = pk2(h[0], h[1]); w.y = pk2(h[2], h[3]);
;                 *(u32x2*)(H + (size_t)r * DM + col) = w; } }
.Lmh_4:
	s_waitcnt vmcnt(8)
	v_lshl_add_u64 v[48:49], v[12:13], 0, s[44:45]
	global_load_dwordx2 v[92:93], v[48:49], off
	global_load_dwordx2 v[94:95], v[48:49], off offset:512
	global_load_dwordx2 v[96:97], v[48:49], off offset:1024
	global_load_dwordx2 v[98:99], v[48:49], off offset:1536
	v_lshlrev_b32_e32 v140, 16, v100
	v_and_b32_e32 v141, 0xffff0000, v100
	v_lshlrev_b32_e32 v142, 16, v101
	v_and_b32_e32 v143, 0xffff0000, v101
	v_lshlrev_b32_e32 v144, 16, v102
	v_and_b32_e32 v145, 0xffff0000, v102
	v_lshlrev_b32_e32 v146, 16, v103
	v_and_b32_e32 v147, 0xffff0000, v103
	v_lshlrev_b32_e32 v148, 16, v104
	v_and_b32_e32 v149, 0xffff0000, v104
	v_lshlrev_b32_e32 v150, 16, v105
	v_and_b32_e32 v151, 0xffff0000, v105
	v_lshlrev_b32_e32 v152, 16, v106
	v_and_b32_e32 v153, 0xffff0000, v106
	v_lshlrev_b32_e32 v154, 16, v107
	v_and_b32_e32 v155, 0xffff0000, v107
	v_add_f32_e32 v0, v140, v141
	v_add_f32_e32 v0, v0, v142
	v_add_f32_e32 v0, v0, v143
	v_add_f32_e32 v0, v0, v144
	v_add_f32_e32 v0, v0, v145
	v_add_f32_e32 v0, v0, v146
	v_add_f32_e32 v0, v0, v147
	v_add_f32_e32 v0, v0, v148
	v_add_f32_e32 v0, v0, v149
	v_add_f32_e32 v0, v0, v150
	v_add_f32_e32 v0, v0, v151
	v_add_f32_e32 v0, v0, v152
	v_add_f32_e32 v0, v0, v153
	v_add_f32_e32 v0, v0, v154
	v_add_f32_e32 v0, v0, v155
	ds_bpermute_b32 v14, v31, v0
	s_waitcnt lgkmcnt(0)
	v_add_f32_e32 v0, v0, v14
	ds_bpermute_b32 v14, v32, v0
	s_waitcnt lgkmcnt(0)
	v_add_f32_e32 v0, v0, v14
	ds_bpermute_b32 v14, v33, v0
	s_waitcnt lgkmcnt(0)
	v_add_f32_e32 v0, v0, v14
	ds_bpermute_b32 v14, v34, v0
	s_waitcnt lgkmcnt(0)
	v_add_f32_e32 v0, v0, v14
	ds_bpermute_b32 v14, v35, v0
	s_waitcnt lgkmcnt(0)
	v_add_f32_e32 v0, v0, v14
	ds_bpermute_b32 v14, v36, v0
	s_waitcnt lgkmcnt(0)
	v_add_f32_e32 v0, v0, v14
	v_fmac_f32_e32 v140, 0xba800000, v0
	v_fmac_f32_e32 v141, 0xba800000, v0
	v_fmac_f32_e32 v142, 0xba800000, v0
	v_fmac_f32_e32 v143, 0xba800000, v0
	v_fmac_f32_e32 v144, 0xba800000, v0
	v_fmac_f32_e32 v145, 0xba800000, v0
	v_fmac_f32_e32 v146, 0xba800000, v0
	v_fmac_f32_e32 v147, 0xba800000, v0
	v_fmac_f32_e32 v148, 0xba800000, v0
	v_fmac_f32_e32 v149, 0xba800000, v0
	v_fmac_f32_e32 v150, 0xba800000, v0
	v_fmac_f32_e32 v151, 0xba800000, v0
	v_fmac_f32_e32 v152, 0xba800000, v0
	v_fmac_f32_e32 v153, 0xba800000, v0
	v_fmac_f32_e32 v154, 0xba800000, v0
	v_fmac_f32_e32 v155, 0xba800000, v0
	v_mul_f32_e32 v15, v140, v140
	v_fmac_f32_e32 v15, v141, v141
	v_fmac_f32_e32 v15, v142, v142
	v_fmac_f32_e32 v15, v143, v143
	v_fmac_f32_e32 v15, v144, v144
	v_fmac_f32_e32 v15, v145, v145
	v_fmac_f32_e32 v15, v146, v146
	v_fmac_f32_e32 v15, v147, v147
	v_fmac_f32_e32 v15, v148, v148
	v_fmac_f32_e32 v15, v149, v149
	v_fmac_f32_e32 v15, v150, v150
	v_fmac_f32_e32 v15, v151, v151
	v_fmac_f32_e32 v15, v152, v152
	v_fmac_f32_e32 v15, v153, v153
	v_fmac_f32_e32 v15, v154, v154
	v_fmac_f32_e32 v15, v155, v155
	ds_bpermute_b32 v14, v31, v15
	s_waitcnt lgkmcnt(0)
	v_add_f32_e32 v15, v15, v14
	ds_bpermute_b32 v14, v32, v15
	s_waitcnt lgkmcnt(0)
	v_add_f32_e32 v15, v15, v14
	ds_bpermute_b32 v14, v33, v15
	s_waitcnt lgkmcnt(0)
	v_add_f32_e32 v15, v15, v14
	ds_bpermute_b32 v14, v34, v15
	s_waitcnt lgkmcnt(0)
	v_add_f32_e32 v15, v15, v14
	ds_bpermute_b32 v14, v35, v15
	s_waitcnt lgkmcnt(0)
	v_add_f32_e32 v15, v15, v14
	ds_bpermute_b32 v14, v36, v15
	s_waitcnt lgkmcnt(0)
	v_add_f32_e32 v15, v15, v14
	v_fmamk_f32 v15, v15, 0x3a800000, v189
	v_rsq_f32_e32 v15, v15
	s_nop 0
	v_mul_f32_e32 v140, v140, v15
	v_mul_f32_e32 v141, v141, v15
	v_mul_f32_e32 v142, v142, v15
	v_mul_f32_e32 v143, v143, v15
	v_mul_f32_e32 v144, v144, v15
	v_mul_f32_e32 v145, v145, v15
	v_mul_f32_e32 v146, v146, v15
	v_mul_f32_e32 v147, v147, v15
	v_mul_f32_e32 v148, v148, v15
	v_mul_f32_e32 v149, v149, v15
	v_mul_f32_e32 v150, v150, v15
	v_mul_f32_e32 v151, v151, v15
	v_mul_f32_e32 v152, v152, v15
	v_mul_f32_e32 v153, v153, v15
	v_mul_f32_e32 v154, v154, v15
	v_mul_f32_e32 v155, v155, v15
	v_fma_f32 v140, v60, v140, v76
	v_fma_f32 v141, v61, v141, v77
	v_fma_f32 v142, v62, v142, v78
	v_fma_f32 v143, v63, v143, v79
	v_fma_f32 v144, v64, v144, v80
	v_fma_f32 v145, v65, v145, v81
	v_fma_f32 v146, v66, v146, v82
	v_fma_f32 v147, v67, v147, v83
	v_fma_f32 v148, v68, v148, v84
	v_fma_f32 v149, v69, v149, v85
	v_fma_f32 v150, v70, v150, v86
	v_fma_f32 v151, v71, v151, v87
	v_fma_f32 v152, v72, v152, v88
	v_fma_f32 v153, v73, v153, v89
	v_fma_f32 v154, v74, v154, v90
	v_fma_f32 v155, v75, v155, v91
	v_cvt_pk_bf16_f32 v16, v140, v141
	v_cvt_pk_bf16_f32 v17, v142, v143
	global_store_dwordx2 v[12:13], v[16:17], off
	v_cvt_pk_bf16_f32 v18, v144, v145
	v_cvt_pk_bf16_f32 v19, v146, v147
	global_store_dwordx2 v[12:13], v[18:19], off offset:512
	v_cvt_pk_bf16_f32 v20, v148, v149
	v_cvt_pk_bf16_f32 v21, v150, v151
	global_store_dwordx2 v[12:13], v[20:21], off offset:1024
	v_cvt_pk_bf16_f32 v22, v152, v153
	v_cvt_pk_bf16_f32 v23, v154, v155
	global_store_dwordx2 v[12:13], v[22:23], off offset:1536
	v_fma_f32 v140, v108, v140, v124
	v_fma_f32 v141, v109, v141, v125
	v_fma_f32 v142, v110, v142, v126
	v_fma_f32 v143, v111, v143, v127
	v_fma_f32 v144, v112, v144, v128
	v_fma_f32 v145, v113, v145, v129
	v_fma_f32 v146, v114, v146, v130
	v_fma_f32 v147, v115, v147, v131
	v_fma_f32 v148, v116, v148, v132
	v_fma_f32 v149, v117, v149, v133
	v_fma_f32 v150, v118, v150, v134
	v_fma_f32 v151, v119, v151, v135
	v_fma_f32 v152, v120, v152, v136
	v_fma_f32 v153, v121, v153, v137
	v_fma_f32 v154, v122, v154, v138
	v_fma_f32 v155, v123, v155, v139
	v_cvt_pk_bf16_f32 v50, v140, v141
	v_cvt_pk_bf16_f32 v51, v142, v143
	global_store_dwordx2 v[10:11], v[50:51], off
	v_cvt_pk_bf16_f32 v52, v144, v145
	v_cvt_pk_bf16_f32 v53, v146, v147
	global_store_dwordx2 v[10:11], v[52:53], off offset:512
	v_cvt_pk_bf16_f32 v54, v148, v149
	v_cvt_pk_bf16_f32 v55, v150, v151
	global_store_dwordx2 v[10:11], v[54:55], off offset:1024
	v_cvt_pk_bf16_f32 v56, v152, v153
	v_cvt_pk_bf16_f32 v57, v154, v155
	global_store_dwordx2 v[10:11], v[56:57], off offset:1536
	v_add_u32_e32 v30, s76, v30
	v_mov_b32_e32 v12, v48
	v_mov_b32_e32 v13, v49
	v_lshl_add_u64 v[10:11], v[10:11], 0, s[44:45]
	v_cmp_lt_i32_e32 vcc, s81, v30
	s_or_b64 s[6:7], vcc, s[6:7]
	s_andn2_b64 exec, exec, s[6:7]
	s_cbranch_execnz .LBB0_415

; DI unsigned pk2(float lo, float hi) { const hwf2_t v = {lo, hi}; const hwbf2_t b = __builtin_convertvector(v, hwbf2_t); return __builtin_bit_cast(unsigned, b); }
; DI float lo16(unsigned w) { return __uint_as_float(w << 16); }
; DI float hi16(unsigned w) { return __uint_as_float(w & 0xffff0000u); }
; DI void ln_pass(CP c, int mode, const float* gam, const float* bet, const float* modsc, const float* modsh, int bid, int nb, bool fin) {
;     ...
;     for (int r = bid * 8 + wave; r < MT; r += nb * 8) {
;         f32x4 v[4];
;         if (mode == 0) { const float* src = r < MP ? c->in[I_XP] + (size_t)r * DM : c->in[I_XS] + (size_t)(r - MP) * DM;
; #pragma unroll
;             for (int i = 0; i < 4; ++i) v[i] = *(const f32x4*)(src + lane * 4 + 256 * i); }
;         else {
; #pragma unroll
;             for (int i = 0; i < 4; ++i) { const u32x2 w = *(const u32x2*)(XB + (size_t)r * DM + lane * 4 + 256 * i); v[i] = (f32x4){lo16(w.x), hi16(w.x), lo16(w.y), hi16(w.y)}; } }
;         if (mode != 1) {
;             float s = 0.f;
; #pragma unroll
;             for (int i = 0; i < 4; ++i) s += v[i][0] + v[i][1] + v[i][2] + v[i][3];
;             const float mean = wave_sum(s) * (1.f / 1024.f); float q = 0.f;
; #pragma unroll
;             for (int i = 0; i < 4; ++i) { const f32x4 d = v[i] - mean; q += d[0] * d[0] + d[1] * d[1] + d[2] * d[2] + d[3] * d[3]; }
;             const float rstd = rsqrtf(wave_sum(q) * (1.f / 1024.f) + 1e-5f);
; #pragma unroll
;             for (int i = 0; i < 4; ++i) { const int col = lane * 4 + 256 * i; const f32x4 g = *(const f32x4*)(gam + col), b = *(const f32x4*)(bet + col);
;                 v[i] = (v[i] - mean) * rstd * g + b;
;                 if (fin) *(f32x4*)(c->out + (size_t)r * DM + col) = v[i];
;                 else { u32x2 w; w.x = pk2(v[i][0], v[i][1]); w.y = pk2(v[i][2], v[i][3]); *(u32x2*)(XB + (size_t)r * DM + col) = w; } }
;         }
;         if (modsc) { const int mr = modrow_of(r);
; #pragma unroll
;             for (int i = 0; i < 4; ++i) { const int col = lane * 4 + 256 * i; const f32x4 sc = *(const f32x4*)(modsc + (size_t)mr * 12288 + col), sh = *(const f32x4*)(modsh + (size_t)mr * 12288 + col);
;                 const f32x4 h = v[i] * (sc + 1.0f) + sh; u32x2 w; w.x = pk2(h[0], h[1]); w.y = pk2(h[2], h[3]);
;                 *(u32x2*)(H + (size_t)r * DM + col) = w; } }
.LBB0_491:
	s_andn2_b64 vcc, exec, s[6:7]
	s_cbranch_vccnz .LBB0_497
	s_cmp_eq_u32 s80, 7
	s_cbranch_scc0 .LBB0_497
	v_mov_b32_e32 v12, v188
	v_readlane_b32 s0, v252, 39
	s_waitcnt vmcnt(0)
	v_ashrrev_i32_e32 v10, 6, v12
	v_readlane_b32 s1, v252, 40
	v_add_u32_e32 v30, s0, v10
	s_movk_i32 s0, 0x4200
	v_cmp_gt_i32_e32 vcc, s0, v30
	s_and_saveexec_b64 s[0:1], vcc
	s_mov_b32 s14, 0x800000
	s_cbranch_execz .LBB0_496
	v_and_b32_e32 v6, 64, v196
	v_add_u32_e32 v6, 64, v6
	v_xor_b32_e32 v7, 32, v196
	v_cmp_lt_i32_e32 vcc, v7, v6
	v_readlane_b32 s6, v254, 32
	v_readlane_b32 s7, v254, 33
	v_cndmask_b32_e32 v7, v196, v7, vcc
	v_lshlrev_b32_e32 v31, 2, v7
	v_xor_b32_e32 v7, 16, v196
	v_cmp_lt_i32_e32 vcc, v7, v6
	s_lshl_b64 s[6:7], s[6:7], 2
	v_readlane_b32 s8, v254, 34
	v_cndmask_b32_e32 v7, v196, v7, vcc
	v_lshlrev_b32_e32 v32, 2, v7
	v_xor_b32_e32 v7, 8, v196
	v_cmp_lt_i32_e32 vcc, v7, v6
	s_load_dwordx4 s[16:19], s[46:47], 0xe8
	v_readlane_b32 s9, v254, 35
	v_cndmask_b32_e32 v7, v196, v7, vcc
	v_lshlrev_b32_e32 v33, 2, v7
	v_xor_b32_e32 v7, 4, v196
	v_cmp_lt_i32_e32 vcc, v7, v6
	s_add_u32 s6, s8, s6
	s_addc_u32 s7, s9, s7
	v_cndmask_b32_e32 v7, v196, v7, vcc
	v_lshlrev_b32_e32 v34, 2, v7
	v_xor_b32_e32 v7, 2, v196
	v_cmp_lt_i32_e32 vcc, v7, v6
	v_readlane_b32 s8, v254, 30
	v_readlane_b32 s9, v254, 31
	v_cndmask_b32_e32 v7, v196, v7, vcc
	s_lshl_b32 s8, s8, 10
	v_lshlrev_b32_e32 v0, 4, v12
	v_lshlrev_b32_e32 v35, 2, v7
	v_xor_b32_e32 v7, 1, v196
	s_ashr_i32 s9, s8, 31
	v_and_b32_e32 v0, 0x3f0, v0
	v_cmp_lt_i32_e32 vcc, v7, v6
	s_lshl_b64 s[8:9], s[8:9], 2
	v_lshl_add_u64 v[8:9], s[6:7], 0, v[0:1]
	v_cndmask_b32_e32 v6, v196, v7, vcc
	s_mov_b64 s[6:7], 0x4000
	s_waitcnt lgkmcnt(0)
	s_add_u32 s12, s18, s8
	v_lshlrev_b32_e32 v36, 2, v6
	v_lshl_add_u64 v[6:7], v[8:9], 0, s[6:7]
	s_mov_b64 s[6:7], 0x3000
	s_addc_u32 s13, s19, s9
	v_lshl_add_u64 v[8:9], v[8:9], 0, s[6:7]
	v_readlane_b32 s6, v252, 39
	s_add_u32 s8, s16, s8
	v_ashrrev_i32_e32 v11, 31, v10
	v_readlane_b32 s7, v252, 40
	s_addc_u32 s9, s17, s9
	v_lshl_add_u64 v[2:3], s[8:9], 0, v[0:1]
	v_lshl_add_u64 v[10:11], s[6:7], 0, v[10:11]
	v_lshl_add_u64 v[4:5], s[12:13], 0, v[0:1]
	v_lshlrev_b64 v[10:11], 11, v[10:11]
	v_and_b32_e32 v0, 63, v12
	v_lshl_or_b32 v10, v0, 3, v10
	v_lshl_add_u64 v[10:11], s[20:21], 0, v[10:11]
	s_mov_b64 s[6:7], 0x123c4000
	v_lshl_add_u64 v[10:11], v[10:11], 0, s[6:7]
	s_mov_b64 s[6:7], 0
	global_load_dwordx4 v[60:63], v[2:3], off
	global_load_dwordx4 v[64:67], v[2:3], off offset:1024
	global_load_dwordx4 v[68:71], v[2:3], off offset:2048
	global_load_dwordx4 v[72:75], v[2:3], off offset:3072
	global_load_dwordx4 v[76:79], v[4:5], off
	global_load_dwordx4 v[80:83], v[4:5], off offset:1024
	global_load_dwordx4 v[84:87], v[4:5], off offset:2048
	global_load_dwordx4 v[88:91], v[4:5], off offset:3072
	v_add_co_u32_e32 v12, vcc, 0xa342000, v10
	s_nop 1
	v_addc_co_u32_e32 v13, vcc, 0, v11, vcc
	global_load_dwordx2 v[92:93], v[12:13], off
	global_load_dwordx2 v[94:95], v[12:13], off offset:512
	global_load_dwordx2 v[96:97], v[12:13], off offset:1024
	global_load_dwordx2 v[98:99], v[12:13], off offset:1536
	global_load_dwordx4 v[108:111], v[6:7], off
	global_load_dwordx4 v[112:115], v[6:7], off offset:1024
	global_load_dwordx4 v[116:119], v[6:7], off offset:2048
	global_load_dwordx4 v[120:123], v[6:7], off offset:3072
	global_load_dwordx4 v[124:127], v[8:9], off
	global_load_dwordx4 v[128:131], v[8:9], off offset:1024
	global_load_dwordx4 v[132:135], v[8:9], off offset:2048
	global_load_dwordx4 v[136:139], v[8:9], off offset:3072
	s_waitcnt vmcnt(0)
	v_add_f32_e32 v108, 1.0, v108
	v_add_f32_e32 v109, 1.0, v109
	v_add_f32_e32 v110, 1.0, v110
	v_add_f32_e32 v111, 1.0, v111
	v_add_f32_e32 v112, 1.0, v112
	v_add_f32_e32 v113, 1.0, v113
	v_add_f32_e32 v114, 1.0, v114
	v_add_f32_e32 v115, 1.0, v115
	v_add_f32_e32 v116, 1.0, v116
	v_add_f32_e32 v117, 1.0, v117
	v_add_f32_e32 v118, 1.0, v118
	v_add_f32_e32 v119, 1.0, v119
	v_add_f32_e32 v120, 1.0, v120
	v_add_f32_e32 v121, 1.0, v121
	v_add_f32_e32 v122, 1.0, v122
	v_add_f32_e32 v123, 1.0, v123
